# pre-phase item loops: loop-top waits no longer wait for the previous item's store acks (counted waits), plus LN epilogue batch merge, mask and wait edits
# baseline (speedup 1.0000x reference)
.LBB0_812:
	s_or_b64 exec, exec, s[6:7]
	v_add_u32_e32 v108, s64, v184
	v_ashrrev_i32_e32 v109, 31, v108
	v_lshl_add_u64 v[16:17], s[72:73], 0, v[108:109]
	v_lshlrev_b64 v[16:17], 7, v[16:17]
	v_lshl_add_u64 v[16:17], s[66:67], 0, v[16:17]
	s_lshl_b32 s38, s5, 2
	s_mov_b32 s39, 0
	v_lshl_add_u64 v[16:17], v[16:17], 0, s[38:39]
	global_load_dword v98, v[16:17], off offset:64
	global_load_dword v90, v[16:17], off offset:80
	s_lshr_b32 s33, s2, 10
	s_add_u32 s89, s48, 0x51b80000
	s_addc_u32 s90, s49, 0
	s_lshl_b32 s2, s4, 3
	v_mov_b32_e32 v16, 0
	s_cmp_eq_u32 s4, 0
	v_mov_b32_e32 v19, v16
	s_movk_i32 s3, 0x90
	v_cmp_lt_i32_e64 s[34:35], -1, v106
	s_cselect_b64 s[40:41], -1, 0
	s_xor_b64 s[28:29], s[28:29], -1
	v_lshl_add_u64 v[110:111], s[60:61], 0, v[18:19]
	v_mul_lo_u32 v17, v20, s3
	v_mul_lo_u32 v19, v21, s3
	v_add_u32_e32 v112, s12, v20
	v_mul_lo_u32 v118, v184, s3
	v_add_u32_e32 v188, s2, v184
	s_and_b64 s[28:29], s[28:29], s[34:35]
	s_add_i32 s34, 0, 0x12000
	s_lshl_b32 s3, s4, 4
	v_cmp_lt_i32_e64 s[30:31], -1, v112
	v_add_u32_e32 v114, 0xc0, v188
	s_xor_b64 s[42:43], vcc, -1
	v_add_u32_e32 v20, s34, v18
	s_add_i32 s35, s34, s3
	s_add_i32 s3, s3, 0
	v_add_u32_e32 v18, 0, v18
	v_mov_b32_e32 v113, v16
	v_mov_b32_e32 v107, v16
	v_cmp_eq_u32_e64 s[6:7], 0, v184
	v_cmp_eq_u32_e64 s[8:9], 1, v184
	v_cmp_eq_u32_e64 s[10:11], 2, v184
	v_cmp_eq_u32_e64 s[12:13], 3, v184
	v_cmp_eq_u32_e64 s[14:15], 4, v184
	v_cmp_eq_u32_e64 s[16:17], 5, v184
	v_cmp_eq_u32_e64 s[18:19], 6, v184
	v_cmp_eq_u32_e64 s[20:21], 7, v184
	v_ashrrev_i32_e32 v185, 31, v184
	v_cmp_gt_i32_e64 s[22:23], 8, v184
	v_ashrrev_i32_e32 v115, 31, v114
	v_ashrrev_i32_e32 v187, 31, v186
	s_and_b64 s[30:31], s[42:43], s[30:31]
	v_writelane_b32 v250, s34, 16
	v_add_u32_e32 v194, s3, v118
	v_mov_b32_e32 v120, 0x3ecc95a3
	v_mov_b32_e32 v121, 0xff800000
	v_mov_b32_e32 v122, 0x1000
	s_mov_b32 s34, 0x3e000000
	v_add_u32_e32 v123, v18, v17
	v_add_u32_e32 v124, v20, v17
	v_add_u32_e32 v125, v20, v19
	v_mov_b32_e32 v126, 0x7f800000
	v_mov_b32_e32 v127, 0x7fc00000
	s_lshl_b32 s54, s2, 2
	s_mov_b32 s50, 0
	s_waitcnt vmcnt(0)
	s_branch .LBB0_814

.LBB0_814:
	s_mov_b64 s[42:43], s[0:1]
	s_mov_b64 s[46:47], s[0:1]
	s_and_saveexec_b64 s[44:45], s[24:25]
	s_cbranch_execz .LBB0_816
	s_waitcnt vmcnt(7)
	ds_write_b128 v124, v[4:7]

.LBB0_819:
	s_waitcnt vmcnt(7)
	ds_write_b128 v125, v[12:15] offset:9648
.LBB0_820:
	s_or_b64 exec, exec, s[46:47]
	s_add_i32 s51, s84, s50
	s_cmpk_eq_i32 s50, 0x700
	s_waitcnt vmcnt(7)
	v_mov_b32_e32 v128, v90
	v_mov_b32_e32 v17, v98
	s_cbranch_scc1 .LBB0_830
	s_add_i32 s3, s51, 0x100
	s_ashr_i32 s46, s3, 9
	s_ashr_i32 s47, s46, 31
	s_bfe_u32 s3, s3, 0x20007
	s_lshl_b64 s[46:47], s[46:47], 13
	s_lshl_b32 s38, s3, 7
	v_mov_b32_e32 v2, v16
	v_mov_b32_e32 v3, v16
	v_lshl_add_u64 v[4:5], s[46:47], 0, v[112:113]
	v_lshl_add_u64 v[8:9], v[110:111], 0, s[38:39]
	s_mov_b64 s[52:53], 0x14000000
	v_mov_b32_e32 v0, v16
	v_mov_b32_e32 v1, v16
	v_lshlrev_b64 v[12:13], 9, v[4:5]
	v_mov_b64_e32 v[6:7], v[2:3]
	v_lshl_add_u64 v[10:11], v[8:9], 0, s[52:53]
	v_mov_b64_e32 v[4:5], v[0:1]
	s_and_saveexec_b64 s[74:75], s[30:31]
	s_cbranch_execz .LBB0_823
	v_lshl_add_u64 v[4:5], v[10:11], 0, v[12:13]
	global_load_dwordx4 v[4:7], v[4:5], off

.LBB0_832:
	s_waitcnt vmcnt(7)
	ds_write_b128 v125, v[0:3]
	s_or_b64 exec, exec, s[46:47]
	s_and_saveexec_b64 s[46:47], s[24:25]
	s_cbranch_execz .LBB0_818
.LBB0_833:
	s_waitcnt vmcnt(7)
	ds_write_b128 v124, v[8:11] offset:9648
	s_or_b64 exec, exec, s[46:47]
	s_and_saveexec_b64 s[46:47], s[26:27]
	s_cbranch_execnz .LBB0_819
	s_branch .LBB0_820

.LBB0_836:
	s_lshl_b64 s[24:25], s[36:37], 22
	s_add_u32 s3, s60, s24
	s_addc_u32 s24, s61, s25
	s_lshl_b32 s26, s85, 15
	s_add_u32 s3, s3, s26
	s_addc_u32 s24, s24, 0
	s_lshl_b32 s25, s33, 7
	s_lshl_b32 s5, s5, 22
	s_and_b32 s5, s5, 0x800000
	s_and_b32 s25, s25, 0x80
	s_or_b32 s5, s5, s25
	v_lshrrev_b32_e32 v0, 28, v187
	s_lshl_b32 s5, s5, 1
	v_add_u32_e32 v0, v186, v0
	s_add_u32 s3, s3, s5
	v_ashrrev_i32_e32 v16, 4, v0
	v_and_b32_e32 v0, -16, v0
	s_addc_u32 s5, s24, 0
	v_sub_u32_e32 v20, v186, v0
	s_add_u32 s24, s3, 0x6000000
	v_lshlrev_b32_e32 v0, 3, v20
	v_ashrrev_i32_e32 v17, 31, v16
	s_addc_u32 s25, s5, 0
	v_lshlrev_b64 v[32:33], 9, v[16:17]
	v_ashrrev_i32_e32 v1, 31, v0
	v_lshl_add_u64 v[2:3], s[24:25], 0, v[32:33]
	v_lshlrev_b64 v[34:35], 1, v[0:1]
	v_lshl_add_u64 v[0:1], v[2:3], 0, v[34:35]
	v_ashrrev_i32_e32 v2, 31, v119
	v_lshrrev_b32_e32 v2, 28, v2
	v_add_u32_e32 v2, v119, v2
	v_ashrrev_i32_e32 v18, 4, v2
	v_and_b32_e32 v2, -16, v2
	v_ashrrev_i32_e32 v19, 31, v18
	v_sub_u32_e32 v17, v119, v2
	v_lshlrev_b64 v[36:37], 9, v[18:19]
	v_lshlrev_b32_e32 v2, 3, v17
	v_lshl_add_u64 v[4:5], s[24:25], 0, v[36:37]
	s_add_u32 s24, s3, 0x8000000
	v_ashrrev_i32_e32 v3, 31, v2
	s_addc_u32 s25, s5, 0
	v_lshlrev_b64 v[38:39], 1, v[2:3]
	v_lshl_add_u64 v[8:9], s[24:25], 0, v[32:33]
	v_lshl_add_u64 v[10:11], s[24:25], 0, v[36:37]
	v_lshl_add_u64 v[4:5], v[4:5], 0, v[38:39]
	v_lshl_add_u64 v[8:9], v[8:9], 0, v[34:35]
	v_lshl_add_u64 v[12:13], v[10:11], 0, v[38:39]
	global_load_dwordx4 v[0:3], v[0:1], off
	s_nop 0
	global_load_dwordx4 v[4:7], v[4:5], off
	s_nop 0
	global_load_dwordx4 v[8:11], v[8:9], off
	s_nop 0
	global_load_dwordx4 v[12:15], v[12:13], off
	v_writelane_b32 v250, s93, 17
	v_writelane_b32 v250, s87, 18
	v_writelane_b32 v250, s94, 19
	s_add_u32 s33, s60, s26
	s_movk_i32 s3, 0x110
	v_writelane_b32 v250, s95, 20
	v_writelane_b32 v250, s88, 21
	s_addc_u32 s50, s61, 0
	v_mul_lo_u32 v19, v16, s3
	v_writelane_b32 v250, s89, 22
	v_writelane_b32 v250, s86, 23
	v_lshlrev_b32_e32 v20, 4, v20
	v_mul_lo_u32 v18, v18, s3
	v_lshlrev_b32_e32 v21, 4, v17
	v_mul_lo_u32 v22, v184, s3
	v_readlane_b32 s46, v250, 16
	s_lshl_b32 s3, s4, 5
	s_mul_i32 s51, s84, 0x10200
	v_add_u32_e32 v23, s46, v19
	v_add_u32_e32 v24, s46, v18
	v_add_u32_e32 v25, s46, v20
	v_add_u32_e32 v26, s46, v21
	s_add_i32 s46, s3, s46
	s_add_i32 s3, s3, 0
	v_add_u32_e32 v62, s46, v22
	v_add_u32_e32 v63, s3, v22
	s_mul_hi_i32 s3, s84, 0x10200
	s_add_u32 s46, s48, s51
	v_lshl_add_u32 v16, s4, 4, v184
	s_addc_u32 s47, s49, s3
	s_lshl_b32 s4, s4, 10
	v_ashrrev_i32_e32 v17, 31, v16
	s_add_u32 s4, s51, s4
	v_lshl_add_u64 v[16:17], v[16:17], 2, s[46:47]
	s_mov_b64 s[46:47], 0x49a90000
	s_addc_u32 s3, s3, 0
	v_lshl_add_u64 v[40:41], v[16:17], 0, s[46:47]
	s_add_u32 s46, s48, s4
	v_add_u32_e32 v22, 0, v19
	v_add_u32_e32 v27, 0, v18
	s_addc_u32 s47, s49, s3
	s_mov_b32 s5, 0x800000
	v_cmp_gt_i32_e64 s[24:25], 32, v184
	v_cmp_gt_i32_e64 s[26:27], 16, v184
	v_cmp_eq_u32_e64 s[28:29], 14, v184
	v_cmp_eq_u32_e64 s[30:31], 13, v184
	v_cmp_eq_u32_e64 s[34:35], 12, v184
	v_cmp_eq_u32_e64 s[36:37], 11, v184
	v_cmp_eq_u32_e64 s[38:39], 10, v184
	v_cmp_eq_u32_e64 s[40:41], 9, v184
	v_cmp_eq_u32_e64 s[42:43], 8, v184
	v_cmp_eq_u32_e64 s[44:45], 15, v184
	v_lshl_add_u64 v[42:43], v[184:185], 4, s[46:47]
	s_add_i32 s4, s84, 0x100
	s_mov_b64 s[74:75], 0
	v_add_u32_e32 v64, v23, v20
	v_add_u32_e32 v65, v24, v21
	v_add_u32_e32 v66, v25, v19
	v_add_u32_e32 v67, v26, v18
	s_mov_b32 s51, 0x3f317217
	s_mov_b32 s52, 0x7f800000
	v_add_u32_e32 v68, v22, v20
	v_add_u32_e32 v69, v27, v21
	v_mov_b32_e32 v70, 0x41b17218
	s_waitcnt vmcnt(0)
	s_branch .LBB0_838

.LBB0_838:
	s_mov_b64 s[46:47], s[0:1]
	s_cmp_eq_u32 s74, 0x70e0000
	s_mov_b64 s[46:47], s[0:1]
	s_waitcnt vmcnt(11)
	ds_write_b128 v64, v[0:3]
	s_waitcnt vmcnt(10)
	ds_write_b128 v65, v[4:7]
	s_waitcnt vmcnt(9)
	ds_write_b128 v66, v[8:11] offset:17408
	s_waitcnt vmcnt(8)
	ds_write_b128 v67, v[12:15] offset:17408
	s_cbranch_scc1 .LBB0_840
	s_ashr_i32 s46, s4, 9
	s_ashr_i32 s47, s46, 31
	s_lshl_b64 s[46:47], s[46:47], 22
	s_add_u32 s3, s33, s46
	s_addc_u32 s46, s50, s47
	s_lshl_b32 s47, s4, 15
	s_and_b32 s47, s47, 0x800000
	s_and_b32 s53, s4, 0x80
	s_or_b32 s47, s47, s53
	s_lshl_b32 s47, s47, 1
	s_add_u32 s3, s3, s47
	s_addc_u32 s53, s46, 0
	s_add_u32 s46, s3, 0x6000000
	s_addc_u32 s47, s53, 0
	v_lshl_add_u64 v[0:1], s[46:47], 0, v[32:33]
	v_lshl_add_u64 v[2:3], s[46:47], 0, v[36:37]
	s_add_u32 s46, s3, 0x8000000
	s_addc_u32 s47, s53, 0
	v_lshl_add_u64 v[8:9], s[46:47], 0, v[32:33]
	v_lshl_add_u64 v[10:11], s[46:47], 0, v[36:37]
	v_lshl_add_u64 v[0:1], v[0:1], 0, v[34:35]
	v_lshl_add_u64 v[4:5], v[2:3], 0, v[38:39]
	v_lshl_add_u64 v[8:9], v[8:9], 0, v[34:35]
	v_lshl_add_u64 v[12:13], v[10:11], 0, v[38:39]
	global_load_dwordx4 v[0:3], v[0:1], off
	s_nop 0
	global_load_dwordx4 v[4:7], v[4:5], off
	s_nop 0
	global_load_dwordx4 v[8:11], v[8:9], off
	s_nop 0
	global_load_dwordx4 v[12:15], v[12:13], off

.LBB0_842:
	s_add_u32 s87, s48, 0x45a00000
	s_addc_u32 s53, s49, 0
	s_or_b32 s72, s72, s64
	s_lshl_b64 s[4:5], s[72:73], 9
	s_waitcnt vmcnt(11)
	v_lshrrev_b32_e32 v0, 29, v187
	s_add_u32 s3, s60, s4
	v_readlane_b32 s4, v250, 14
	v_add_u32_e32 v0, v186, v0
	s_addc_u32 s5, s61, s5
	s_lshl_b32 s4, s4, 1
	s_waitcnt vmcnt(9)
	v_ashrrev_i32_e32 v8, 3, v0
	v_and_b32_e32 v0, -8, v0
	s_add_u32 s4, s3, s4
	v_sub_u32_e32 v10, v186, v0
	v_ashrrev_i32_e32 v9, 31, v8
	s_addc_u32 s5, s5, 0
	v_lshlrev_b32_e32 v190, 3, v10
	v_lshlrev_b64 v[192:193], 9, v[8:9]
	v_lshl_add_u64 v[0:1], s[4:5], 0, v[192:193]
	v_ashrrev_i32_e32 v191, 31, v190
	v_lshl_add_u64 v[0:1], v[190:191], 1, v[0:1]
	s_mov_b32 s3, 0x1000000
	v_lshl_add_u64 v[2:3], s[72:73], 0, v[184:185]
	v_add_co_u32_e32 v4, vcc, s3, v0
	v_lshlrev_b64 v[2:3], 7, v[2:3]
	s_nop 0
	v_addc_co_u32_e32 v5, vcc, 0, v1, vcc
	v_lshl_add_u64 v[2:3], s[66:67], 0, v[2:3]
	global_load_dwordx4 v[28:31], v[2:3], off offset:48
	global_load_dwordx4 v[32:35], v[2:3], off offset:32
	global_load_dwordx4 v[36:39], v[2:3], off offset:16
	global_load_dwordx4 v[40:43], v[2:3], off
	s_nop 0
	global_load_dwordx4 v[0:3], v[0:1], off
	s_nop 0
	global_load_dwordx4 v[4:7], v[4:5], off
	s_movk_i32 s4, 0x90
	v_lshlrev_b32_e32 v9, 4, v10
	v_mul_lo_u32 v8, v8, s4
	v_readlane_b32 s4, v250, 16
	s_lshl_b32 s2, s2, 1
	s_mov_b32 s65, 0
	v_add_u32_e32 v10, s4, v9
	v_add_u32_e32 v9, 0, v9
	v_add_u32_e32 v196, v10, v8
	s_add_i32 s2, s2, s4
	v_add_u32_e32 v202, v9, v8
	v_readlane_b32 s26, v250, 21
	v_readlane_b32 s78, v250, 19
	v_ashrrev_i32_e32 v189, 31, v188
	v_add_u32_e32 v195, s2, v118
	v_mov_b32_e32 v197, 0
	v_mov_b32_e32 v198, 0x1000
	v_mov_b32_e32 v199, 0x2000
	v_mov_b32_e32 v200, 0x3000
	s_mov_b32 s2, 0xbfb8aa3b
	s_mov_b32 s4, 0x3f2aaaab
	v_mov_b32_e32 v201, 0x3ecc95a3
	s_mov_b32 s5, 0x3f317218
	s_mov_b32 s33, 0x7f800000
	s_mov_b32 s34, 0x33800000
	v_mov_b32_e32 v203, 0x7f800000
	v_mov_b32_e32 v204, 0x7fc00000
	v_mov_b32_e32 v205, 0xff800000
	s_mov_b32 s35, s65
	v_readlane_b32 s80, v250, 23
	s_mov_b32 s56, s26
	v_readlane_b32 s79, v250, 20
	v_readlane_b32 s86, v250, 18
	v_readlane_b32 s44, v250, 17
	v_readlane_b32 s45, v250, 13
	v_readlane_b32 s46, v250, 12
	v_readlane_b32 s27, v250, 22
	s_waitcnt vmcnt(5)
	v_mov_b64_e32 v[8:9], v[28:29]
	s_waitcnt vmcnt(4)
	v_mov_b64_e32 v[12:13], v[32:33]
	s_waitcnt vmcnt(3)
	v_mov_b64_e32 v[16:17], v[36:37]
	s_waitcnt vmcnt(2)
	v_mov_b64_e32 v[20:21], v[40:41]
	v_mov_b64_e32 v[10:11], v[30:31]
	v_mov_b64_e32 v[14:15], v[34:35]
	v_mov_b64_e32 v[18:19], v[38:39]
	v_mov_b64_e32 v[22:23], v[42:43]
	s_waitcnt vmcnt(0)
	s_branch .LBB0_844

.LBB0_844:
	s_mov_b64 s[26:27], s[0:1]
	s_mov_b64 s[28:29], s[0:1]
	s_load_dwordx2 s[26:27], s[26:27], 0x40
	s_load_dwordx2 s[28:29], s[28:29], 0x48
	s_add_i32 s36, s84, s35
	s_cmpk_eq_i32 s35, 0x700
	s_waitcnt vmcnt(5)
	ds_write_b128 v196, v[0:3]
	s_waitcnt vmcnt(5)
	ds_write_b128 v196, v[4:7] offset:9216
	s_cbranch_scc1 .LBB0_846
	s_add_i32 s37, s36, 0x100
	s_ashr_i32 s30, s37, 9
	s_ashr_i32 s31, s30, 31
	s_lshl_b64 s[30:31], s[30:31], 13
	s_or_b64 s[30:31], s[30:31], s[64:65]
	s_lshl_b64 s[38:39], s[30:31], 9
	s_add_u32 s38, s60, s38
	s_addc_u32 s39, s61, s39
	s_and_b32 s37, s37, 0x180
	s_add_u32 s38, s38, s37
	s_addc_u32 s39, s39, 0
	v_lshl_add_u64 v[0:1], s[38:39], 0, v[192:193]
	v_lshl_add_u64 v[0:1], v[190:191], 1, v[0:1]
	v_lshl_add_u64 v[8:9], s[30:31], 0, v[184:185]
	v_add_co_u32_e32 v4, vcc, s3, v0
	v_lshlrev_b64 v[8:9], 7, v[8:9]
	s_nop 0
	v_addc_co_u32_e32 v5, vcc, 0, v1, vcc
	v_lshl_add_u64 v[20:21], s[66:67], 0, v[8:9]
	global_load_dwordx4 v[0:3], v[0:1], off
	s_nop 0
	global_load_dwordx4 v[4:7], v[4:5], off
	s_nop 0
	global_load_dwordx4 v[8:11], v[20:21], off offset:48
	global_load_dwordx4 v[12:15], v[20:21], off offset:32
	global_load_dwordx4 v[16:19], v[20:21], off offset:16
	s_nop 0
	global_load_dwordx4 v[20:23], v[20:21], off

.LBB0_2087:
	s_or_b64 exec, exec, s[6:7]
	v_add_u32_e32 v108, s72, v184
	v_ashrrev_i32_e32 v109, 31, v108
	v_lshl_add_u64 v[16:17], s[74:75], 0, v[108:109]
	v_lshlrev_b64 v[16:17], 7, v[16:17]
	v_lshl_add_u64 v[16:17], s[66:67], 0, v[16:17]
	s_lshl_b32 s38, s33, 2
	s_mov_b32 s39, 0
	v_lshl_add_u64 v[16:17], v[16:17], 0, s[38:39]
	global_load_dword v90, v[16:17], off offset:64
	global_load_dword v54, v[16:17], off offset:80
	s_lshr_b32 s50, s76, 10
	v_mov_b32_e32 v16, 0
	s_lshl_b32 s2, s5, 3
	v_mov_b32_e32 v19, v16
	s_movk_i32 s4, 0x90
	s_cmp_eq_u32 s5, 0
	v_lshl_add_u64 v[110:111], s[60:61], 0, v[18:19]
	v_mul_lo_u32 v17, v20, s4
	v_mul_lo_u32 v19, v21, s4
	v_add_u32_e32 v112, s3, v20
	v_cmp_lt_i32_e64 s[34:35], -1, v106
	v_mul_lo_u32 v118, v184, s4
	s_cselect_b64 s[40:41], -1, 0
	v_add_u32_e32 v188, s2, v184
	s_xor_b64 s[28:29], s[28:29], -1
	v_readlane_b32 s3, v250, 16
	s_lshl_b32 s4, s5, 4
	v_cmp_lt_i32_e64 s[30:31], -1, v112
	v_add_u32_e32 v114, 0xc0, v188
	s_xor_b64 s[42:43], vcc, -1
	s_and_b64 s[28:29], s[28:29], s[34:35]
	v_add_u32_e32 v20, s3, v18
	s_add_i32 s35, s3, s4
	s_add_i32 s3, s4, 0
	v_add_u32_e32 v18, 0, v18
	v_mov_b32_e32 v113, v16
	v_mov_b32_e32 v107, v16
	v_cmp_eq_u32_e64 s[6:7], 0, v184
	v_cmp_eq_u32_e64 s[8:9], 1, v184
	v_cmp_eq_u32_e64 s[10:11], 2, v184
	v_cmp_eq_u32_e64 s[12:13], 3, v184
	v_cmp_eq_u32_e64 s[14:15], 4, v184
	v_cmp_eq_u32_e64 s[16:17], 5, v184
	v_cmp_eq_u32_e64 s[18:19], 6, v184
	v_cmp_eq_u32_e64 s[20:21], 7, v184
	v_ashrrev_i32_e32 v185, 31, v184
	v_cmp_gt_i32_e64 s[22:23], 8, v184
	v_ashrrev_i32_e32 v115, 31, v114
	v_ashrrev_i32_e32 v187, 31, v186
	s_and_b64 s[30:31], s[42:43], s[30:31]
	v_add_u32_e32 v194, s3, v118
	v_mov_b32_e32 v120, 0x3ecc95a3
	v_mov_b32_e32 v121, 0xff800000
	v_mov_b32_e32 v122, 0x3000
	v_mov_b32_e32 v123, 0x2000
	s_mov_b32 s34, 0x3e000000
	v_add_u32_e32 v124, v18, v17
	v_add_u32_e32 v125, v20, v17
	v_add_u32_e32 v126, v20, v19
	v_mov_b32_e32 v127, 0x7f800000
	v_mov_b32_e32 v128, 0x7fc00000
	s_lshl_b32 s54, s2, 2
	s_mov_b32 s51, 0
	s_waitcnt vmcnt(0)
	s_branch .LBB0_2089

.LBB0_2089:
	s_mov_b64 s[42:43], s[0:1]
	s_mov_b64 s[44:45], s[0:1]
	s_and_saveexec_b64 s[46:47], s[24:25]
	s_cbranch_execz .LBB0_2091
	s_waitcnt vmcnt(7)
	ds_write_b128 v125, v[4:7]

.LBB0_2094:
	s_waitcnt vmcnt(7)
	ds_write_b128 v126, v[12:15] offset:9648
.LBB0_2095:
	s_or_b64 exec, exec, s[46:47]
	s_add_i32 s52, s96, s51
	s_cmpk_eq_i32 s51, 0x700
	s_waitcnt vmcnt(7)
	v_mov_b32_e32 v129, v54
	v_mov_b32_e32 v17, v90
	s_cbranch_scc1 .LBB0_2105
	s_add_i32 s3, s52, 0x100
	s_ashr_i32 s46, s3, 9
	s_ashr_i32 s47, s46, 31
	s_bfe_u32 s3, s3, 0x20007
	s_lshl_b64 s[46:47], s[46:47], 13
	s_lshl_b32 s38, s3, 7
	v_mov_b32_e32 v2, v16
	v_mov_b32_e32 v3, v16
	v_lshl_add_u64 v[4:5], s[46:47], 0, v[112:113]
	v_lshl_add_u64 v[8:9], v[110:111], 0, s[38:39]
	s_mov_b64 s[68:69], 0x14000000
	v_mov_b32_e32 v0, v16
	v_mov_b32_e32 v1, v16
	v_lshlrev_b64 v[12:13], 9, v[4:5]
	v_mov_b64_e32 v[6:7], v[2:3]
	v_lshl_add_u64 v[10:11], v[8:9], 0, s[68:69]
	v_mov_b64_e32 v[4:5], v[0:1]
	s_and_saveexec_b64 s[76:77], s[30:31]
	s_cbranch_execz .LBB0_2098
	v_lshl_add_u64 v[4:5], v[10:11], 0, v[12:13]
	global_load_dwordx4 v[4:7], v[4:5], off

.LBB0_2107:
	s_waitcnt vmcnt(7)
	ds_write_b128 v126, v[0:3]
	s_or_b64 exec, exec, s[46:47]
	s_and_saveexec_b64 s[46:47], s[24:25]
	s_cbranch_execz .LBB0_2093
.LBB0_2108:
	s_waitcnt vmcnt(7)
	ds_write_b128 v125, v[8:11] offset:9648
	s_or_b64 exec, exec, s[46:47]
	s_and_saveexec_b64 s[46:47], s[26:27]
	s_cbranch_execnz .LBB0_2094
	s_branch .LBB0_2095

.LBB0_2111:
	s_lshl_b64 s[24:25], s[36:37], 22
	s_add_u32 s3, s60, s24
	s_addc_u32 s24, s61, s25
	s_lshl_b32 s26, s97, 15
	s_add_u32 s3, s3, s26
	s_addc_u32 s24, s24, 0
	s_lshl_b32 s25, s50, 7
	s_lshl_b32 s27, s33, 22
	s_and_b32 s27, s27, 0x800000
	s_and_b32 s25, s25, 0x80
	s_or_b32 s25, s27, s25
	v_lshrrev_b32_e32 v0, 28, v187
	s_lshl_b32 s25, s25, 1
	v_add_u32_e32 v0, v186, v0
	s_add_u32 s3, s3, s25
	v_ashrrev_i32_e32 v16, 4, v0
	v_and_b32_e32 v0, -16, v0
	s_addc_u32 s27, s24, 0
	v_sub_u32_e32 v20, v186, v0
	s_add_u32 s24, s3, 0x6000000
	v_lshlrev_b32_e32 v0, 3, v20
	v_ashrrev_i32_e32 v17, 31, v16
	s_addc_u32 s25, s27, 0
	v_lshlrev_b64 v[48:49], 9, v[16:17]
	v_ashrrev_i32_e32 v1, 31, v0
	v_lshl_add_u64 v[2:3], s[24:25], 0, v[48:49]
	v_lshlrev_b64 v[50:51], 1, v[0:1]
	v_lshl_add_u64 v[0:1], v[2:3], 0, v[50:51]
	v_ashrrev_i32_e32 v2, 31, v119
	v_lshrrev_b32_e32 v2, 28, v2
	v_add_u32_e32 v2, v119, v2
	v_ashrrev_i32_e32 v18, 4, v2
	v_and_b32_e32 v2, -16, v2
	v_ashrrev_i32_e32 v19, 31, v18
	v_sub_u32_e32 v17, v119, v2
	v_lshlrev_b64 v[52:53], 9, v[18:19]
	v_lshlrev_b32_e32 v2, 3, v17
	v_lshl_add_u64 v[4:5], s[24:25], 0, v[52:53]
	s_add_u32 s24, s3, 0x8000000
	v_ashrrev_i32_e32 v3, 31, v2
	s_addc_u32 s25, s27, 0
	v_lshlrev_b64 v[54:55], 1, v[2:3]
	v_lshl_add_u64 v[8:9], s[24:25], 0, v[48:49]
	v_lshl_add_u64 v[10:11], s[24:25], 0, v[52:53]
	v_lshl_add_u64 v[4:5], v[4:5], 0, v[54:55]
	v_lshl_add_u64 v[8:9], v[8:9], 0, v[50:51]
	v_lshl_add_u64 v[12:13], v[10:11], 0, v[54:55]
	global_load_dwordx4 v[0:3], v[0:1], off
	s_nop 0
	global_load_dwordx4 v[4:7], v[4:5], off
	s_nop 0
	global_load_dwordx4 v[8:11], v[8:9], off
	s_nop 0
	global_load_dwordx4 v[12:15], v[12:13], off
	v_writelane_b32 v250, s94, 27
	s_add_u32 s51, s60, s26
	s_movk_i32 s3, 0x110
	v_writelane_b32 v250, s95, 28
	s_addc_u32 s52, s61, 0
	v_mul_lo_u32 v16, v16, s3
	v_lshlrev_b32_e32 v19, 4, v20
	v_mul_lo_u32 v18, v18, s3
	v_mul_lo_u32 v20, v184, s3
	v_readlane_b32 s46, v250, 16
	s_lshl_b32 s3, s5, 5
	v_lshlrev_b32_e32 v17, 4, v17
	s_add_i32 s5, s3, s46
	s_add_i32 s3, s3, 0
	v_add_u32_e32 v56, s4, v184
	v_add_u32_e32 v21, s46, v16
	v_add_u32_e32 v22, s46, v18
	v_add_u32_e32 v23, s46, v19
	v_add_u32_e32 v24, s46, v17
	v_add_u32_e32 v74, s5, v20
	v_add_u32_e32 v75, s3, v20
	v_add_u32_e32 v20, 0, v16
	v_add_u32_e32 v25, 0, v18
	s_mov_b32 s33, 0
	s_mov_b32 s50, 0x800000
	v_cmp_gt_i32_e64 s[24:25], 32, v184
	v_cmp_gt_i32_e64 s[26:27], 16, v184
	v_cmp_eq_u32_e64 s[28:29], 14, v184
	v_cmp_eq_u32_e64 s[30:31], 13, v184
	v_cmp_eq_u32_e64 s[34:35], 12, v184
	v_cmp_eq_u32_e64 s[36:37], 11, v184
	v_cmp_eq_u32_e64 s[38:39], 10, v184
	v_cmp_eq_u32_e64 s[40:41], 9, v184
	v_cmp_eq_u32_e64 s[42:43], 8, v184
	v_cmp_eq_u32_e64 s[44:45], 15, v184
	v_ashrrev_i32_e32 v57, 31, v56
	v_add_u32_e32 v76, v21, v19
	v_add_u32_e32 v77, v22, v17
	v_add_u32_e32 v78, v23, v16
	v_add_u32_e32 v79, v24, v18
	s_mov_b32 s5, 0x3f317217
	s_mov_b32 s53, 0x7f800000
	v_add_u32_e32 v80, v20, v19
	v_add_u32_e32 v81, v25, v17
	v_mov_b32_e32 v82, 0x3f7fffef
	v_mov_b32_e32 v83, 0x41b17218
	s_waitcnt vmcnt(0)
	s_branch .LBB0_2113

.LBB0_2113:
	s_mov_b64 s[46:47], s[0:1]
	s_mov_b64 s[68:69], s[0:1]
	s_load_dwordx2 s[46:47], s[46:47], 0x58
	s_load_dwordx2 s[76:77], s[68:69], 0x58
	s_add_i32 s55, s96, s33
	s_cmpk_eq_i32 s33, 0x700
	s_waitcnt vmcnt(11)
	ds_write_b128 v76, v[0:3]
	s_waitcnt vmcnt(10)
	ds_write_b128 v77, v[4:7]
	s_waitcnt vmcnt(9)
	ds_write_b128 v78, v[8:11] offset:17408
	s_waitcnt vmcnt(8)
	ds_write_b128 v79, v[12:15] offset:17408
	s_cbranch_scc1 .LBB0_2115
	s_add_i32 s3, s55, 0x100
	s_ashr_i32 s68, s3, 9
	s_ashr_i32 s69, s68, 31
	s_lshl_b64 s[68:69], s[68:69], 22
	s_add_u32 s56, s51, s68
	s_addc_u32 s68, s52, s69
	s_lshl_b32 s69, s3, 15
	s_and_b32 s69, s69, 0x800000
	s_and_b32 s3, s3, 0x80
	s_or_b32 s3, s69, s3
	s_lshl_b32 s3, s3, 1
	s_add_u32 s3, s56, s3
	s_addc_u32 s56, s68, 0
	s_add_u32 s68, s3, 0x6000000
	s_addc_u32 s69, s56, 0
	v_lshl_add_u64 v[0:1], s[68:69], 0, v[48:49]
	v_lshl_add_u64 v[2:3], s[68:69], 0, v[52:53]
	s_add_u32 s68, s3, 0x8000000
	s_addc_u32 s69, s56, 0
	v_lshl_add_u64 v[8:9], s[68:69], 0, v[48:49]
	v_lshl_add_u64 v[10:11], s[68:69], 0, v[52:53]
	v_lshl_add_u64 v[0:1], v[0:1], 0, v[50:51]
	v_lshl_add_u64 v[4:5], v[2:3], 0, v[54:55]
	v_lshl_add_u64 v[8:9], v[8:9], 0, v[50:51]
	v_lshl_add_u64 v[12:13], v[10:11], 0, v[54:55]
	global_load_dwordx4 v[0:3], v[0:1], off
	s_nop 0
	global_load_dwordx4 v[4:7], v[4:5], off
	s_nop 0
	global_load_dwordx4 v[8:11], v[8:9], off
	s_nop 0
	global_load_dwordx4 v[12:15], v[12:13], off

.LBB0_2117:
	s_or_b32 s74, s74, s72
	s_lshl_b64 s[4:5], s[74:75], 9
	v_lshrrev_b32_e32 v0, 29, v187
	s_add_u32 s3, s60, s4
	v_readlane_b32 s4, v250, 26
	v_add_u32_e32 v0, v186, v0
	s_addc_u32 s5, s61, s5
	s_lshl_b32 s4, s4, 1
	v_ashrrev_i32_e32 v8, 3, v0
	v_and_b32_e32 v0, -8, v0
	s_add_u32 s4, s3, s4
	v_sub_u32_e32 v10, v186, v0
	v_ashrrev_i32_e32 v9, 31, v8
	s_addc_u32 s5, s5, 0
	v_lshlrev_b32_e32 v190, 3, v10
	v_lshlrev_b64 v[192:193], 9, v[8:9]
	v_lshl_add_u64 v[0:1], s[4:5], 0, v[192:193]
	v_ashrrev_i32_e32 v191, 31, v190
	v_lshl_add_u64 v[0:1], v[190:191], 1, v[0:1]
	s_mov_b32 s3, 0x1000000
	v_lshl_add_u64 v[2:3], s[74:75], 0, v[184:185]
	v_add_co_u32_e32 v4, vcc, s3, v0
	v_lshlrev_b64 v[2:3], 7, v[2:3]
	s_nop 0
	v_addc_co_u32_e32 v5, vcc, 0, v1, vcc
	v_lshl_add_u64 v[2:3], s[66:67], 0, v[2:3]
	global_load_dwordx4 v[24:27], v[2:3], off offset:48
	global_load_dwordx4 v[32:35], v[2:3], off offset:32
	global_load_dwordx4 v[36:39], v[2:3], off offset:16
	global_load_dwordx4 v[40:43], v[2:3], off
	s_nop 0
	global_load_dwordx4 v[0:3], v[0:1], off
	s_nop 0
	global_load_dwordx4 v[4:7], v[4:5], off
	s_movk_i32 s4, 0x90
	v_lshlrev_b32_e32 v9, 4, v10
	v_mul_lo_u32 v8, v8, s4
	v_readlane_b32 s4, v250, 16
	s_lshl_b32 s2, s2, 1
	s_mov_b32 s73, 0
	v_add_u32_e32 v10, s4, v9
	v_add_u32_e32 v9, 0, v9
	v_add_u32_e32 v196, v10, v8
	s_add_i32 s2, s2, s4
	v_add_u32_e32 v203, v9, v8
	v_readlane_b32 s84, v250, 19
	v_readlane_b32 s94, v250, 27
	v_ashrrev_i32_e32 v189, 31, v188
	v_add_u32_e32 v195, s2, v118
	v_mov_b32_e32 v197, 0
	v_mov_b32_e32 v198, 0x4000
	v_mov_b32_e32 v199, 0x5000
	v_mov_b32_e32 v200, 0x6000
	v_mov_b32_e32 v201, 0x7000
	s_mov_b32 s2, 0xbfb8aa3b
	s_mov_b32 s4, 0x3f2aaaab
	v_mov_b32_e32 v202, 0x3ecc95a3
	s_mov_b32 s5, 0x3f317218
	s_mov_b32 s30, 0x7f800000
	s_mov_b32 s31, 0x33800000
	v_mov_b32_e32 v204, 0x7f800000
	v_mov_b32_e32 v205, 0x7fc00000
	v_mov_b32_e32 v206, 0xff800000
	s_mov_b32 s33, s73
	v_readlane_b32 s76, v250, 23
	v_readlane_b32 s78, v250, 21
	v_readlane_b32 s85, v250, 20
	v_readlane_b32 s77, v250, 18
	v_readlane_b32 s80, v250, 7
	v_readlane_b32 s86, v250, 8
	v_readlane_b32 s52, v250, 25
	v_readlane_b32 s53, v250, 24
	v_readlane_b32 s95, v250, 28
	v_readlane_b32 s79, v250, 22
	s_waitcnt vmcnt(5)
	v_mov_b64_e32 v[8:9], v[24:25]
	s_waitcnt vmcnt(4)
	v_mov_b64_e32 v[12:13], v[32:33]
	s_waitcnt vmcnt(3)
	v_mov_b64_e32 v[16:17], v[36:37]
	s_waitcnt vmcnt(2)
	v_mov_b64_e32 v[20:21], v[40:41]
	v_mov_b64_e32 v[10:11], v[26:27]
	v_mov_b64_e32 v[14:15], v[34:35]
	v_mov_b64_e32 v[18:19], v[38:39]
	v_mov_b64_e32 v[22:23], v[42:43]
	s_waitcnt vmcnt(0)
	s_branch .LBB0_2119

.LBB0_2119:
	s_mov_b64 s[26:27], s[0:1]
	s_load_dwordx2 s[28:29], s[26:27], 0x40
	s_mov_b64 s[26:27], s[0:1]
	s_load_dwordx2 s[26:27], s[26:27], 0x48
	s_add_i32 s34, s96, s33
	s_cmpk_eq_i32 s33, 0x700
	s_waitcnt vmcnt(5)
	ds_write_b128 v196, v[0:3]
	s_waitcnt vmcnt(5)
	ds_write_b128 v196, v[4:7] offset:9216
	s_cbranch_scc1 .LBB0_2121
	s_add_i32 s35, s34, 0x100
	s_ashr_i32 s36, s35, 9
	s_ashr_i32 s37, s36, 31
	s_lshl_b64 s[36:37], s[36:37], 13
	s_or_b64 s[36:37], s[36:37], s[72:73]
	s_lshl_b64 s[38:39], s[36:37], 9
	s_add_u32 s38, s60, s38
	s_addc_u32 s39, s61, s39
	s_and_b32 s35, s35, 0x180
	s_add_u32 s38, s38, s35
	s_addc_u32 s39, s39, 0
	v_lshl_add_u64 v[0:1], s[38:39], 0, v[192:193]
	v_lshl_add_u64 v[0:1], v[190:191], 1, v[0:1]
	v_lshl_add_u64 v[8:9], s[36:37], 0, v[184:185]
	v_add_co_u32_e32 v4, vcc, s3, v0
	v_lshlrev_b64 v[8:9], 7, v[8:9]
	s_nop 0
	v_addc_co_u32_e32 v5, vcc, 0, v1, vcc
	v_lshl_add_u64 v[20:21], s[66:67], 0, v[8:9]
	global_load_dwordx4 v[0:3], v[0:1], off
	s_nop 0
	global_load_dwordx4 v[4:7], v[4:5], off
	s_nop 0
	global_load_dwordx4 v[8:11], v[20:21], off offset:48
	global_load_dwordx4 v[12:15], v[20:21], off offset:32
	global_load_dwordx4 v[16:19], v[20:21], off offset:16
	s_nop 0
	global_load_dwordx4 v[20:23], v[20:21], off
